# on top of v137: GEMM0 V^T epilogue lane^1 exchanges as DPP quad_perm instead of ds_bpermute
# baseline (speedup 1.0000x reference)
;     __device__ __forceinline__ void operator()(const f32x4 (&acc)[2][2][4][2], const Unit& u, int wr, int wc, int fr, int fq) const {
;     ...
;             for (int m = 0; m < 4; ++m) part[ai][m] = *(const f32x4*)(rss + (size_t)(u.pm * BM + ai * HALF + wr * 64 + m * 16 + fr) * 16 + 4 * fq);
;         float rstdv[2][4];
; #pragma unroll
;         for (int ai = 0; ai < 2; ++ai)
; #pragma unroll
;             for (int m = 0; m < 4; ++m) {
;                 float s = (part[ai][m][0] + part[ai][m][1]) + (part[ai][m][2] + part[ai][m][3]);
;                 s += __shfl_xor(s, 16); s += __shfl_xor(s, 32);
;                 rstdv[ai][m] = rsqrtf(s * (1.0f / 1024.0f) + RMS_EPS);
;             }
; #pragma unroll
;         for (int ai = 0; ai < 2; ++ai)
; #pragma unroll
;             for (int m = 0; m < 4; ++m) {
;                 const int row = u.pm * BM + ai * HALF + wr * 64 + m * 16 + fr;
;                 const float rstd = rstdv[ai][m];
;                 const int b = row >> 11, s = row & 2047;
; #pragma unroll
;                 for (int bj = 0; bj < 2; ++bj) {
;                     const int tn = 2 * u.pn + bj;
;                     const int cw = 32 * wc + 8 * fq;
;                     const f32x4 v0 = acc[ai][bj][m][0] * rstd, v1 = acc[ai][bj][m][1] * rstd;
;                     u32x4 w; w.x = ::cvt_pk_bf16(v0[0], v0[1]); w.y = ::cvt_pk_bf16(v0[2], v0[3]); w.z = ::cvt_pk_bf16(v1[0], v1[1]); w.w = ::cvt_pk_bf16(v1[2], v1[3]);
;                     if (tn < 24) {
;                         bf16_t* dst;
;                         if (tn < 8) dst = z + (size_t)(tn >> 2) * ZS_KD + ((size_t)((b * 4 + (tn & 3)) * 2048 + s)) * 128 + cw;
;                         else if (tn < 16) dst = z + ZS_QN + (size_t)((tn - 8) >> 2) * (ZS_KN - ZS_QN) + ((size_t)((b * 8 + ((tn - 8) & 3) * 2 + (cw >> 6)) * 2048 + s)) * 64 + (cw & 63);
;                         else dst = z + ZS_GATE + (size_t)row * 1024 + (tn - 16) * 128 + cw;
;                         *(u32x4*)dst = w;
;                     } else {
;                         const unsigned ox = __shfl_xor(w.x, 1), oy = __shfl_xor(w.y, 1), oz = __shfl_xor(w.z, 1), ow = __shfl_xor(w.w, 1);
;                         const bool odd = fr & 1;
;                         const unsigned a0 = odd ? oz : w.x, a1 = odd ? ow : w.y;
;                         const unsigned b0 = odd ? w.z : ox, b1 = odd ? w.w : oy;
.LBB0_119:
	s_lshl_b32 s33, s10, 8
	v_add_u32_e32 v128, s33, v167
	v_ashrrev_i32_e32 v129, 31, v128
	v_lshlrev_b64 v[130:131], 6, v[128:129]
	v_lshl_add_u64 v[130:131], v[168:169], 0, v[130:131]
	global_load_dwordx4 v[174:177], v[130:131], off
	v_or_b32_e32 v130, 16, v128
	v_ashrrev_i32_e32 v131, 31, v130
	v_lshlrev_b64 v[130:131], 6, v[130:131]
	v_lshl_add_u64 v[130:131], v[168:169], 0, v[130:131]
	global_load_dwordx4 v[178:181], v[130:131], off
	v_or_b32_e32 v130, 32, v128
	v_ashrrev_i32_e32 v131, 31, v130
	v_lshlrev_b64 v[130:131], 6, v[130:131]
	v_lshl_add_u64 v[130:131], v[168:169], 0, v[130:131]
	global_load_dwordx4 v[188:191], v[130:131], off
	v_or_b32_e32 v130, 48, v128
	v_ashrrev_i32_e32 v131, 31, v130
	v_lshlrev_b64 v[130:131], 6, v[130:131]
	v_lshl_add_u64 v[130:131], v[168:169], 0, v[130:131]
	global_load_dwordx4 v[192:195], v[130:131], off
	v_add_u32_e32 v130, 0x80, v128
	v_ashrrev_i32_e32 v131, 31, v130
	v_lshlrev_b64 v[130:131], 6, v[130:131]
	v_lshl_add_u64 v[130:131], v[168:169], 0, v[130:131]
	global_load_dwordx4 v[136:139], v[130:131], off
	v_add_u32_e32 v130, 0x90, v128
	v_ashrrev_i32_e32 v131, 31, v130
	v_lshlrev_b64 v[130:131], 6, v[130:131]
	v_lshl_add_u64 v[130:131], v[168:169], 0, v[130:131]
	global_load_dwordx4 v[140:143], v[130:131], off
	v_add_u32_e32 v130, 0xa0, v128
	v_add_u32_e32 v128, 0xb0, v128
	v_ashrrev_i32_e32 v131, 31, v130
	v_ashrrev_i32_e32 v129, 31, v128
	v_lshlrev_b64 v[130:131], 6, v[130:131]
	v_lshlrev_b64 v[128:129], 6, v[128:129]
	v_lshl_add_u64 v[130:131], v[168:169], 0, v[130:131]
	v_lshl_add_u64 v[128:129], v[168:169], 0, v[128:129]
	global_load_dwordx4 v[132:135], v[130:131], off
	v_and_b32_e32 v156, 64, v240
	global_load_dwordx4 v[128:131], v[128:129], off
	v_xor_b32_e32 v152, 16, v240
	v_add_u32_e32 v186, 64, v156
	v_cmp_lt_i32_e32 vcc, v152, v186
	v_xor_b32_e32 v156, 32, v240
	s_mov_b32 s0, 0x3a800000
	v_cndmask_b32_e32 v152, v240, v152, vcc
	v_lshlrev_b32_e32 v152, 2, v152
	v_cmp_lt_i32_e32 vcc, v156, v186
	s_add_i32 s33, s33, s35
	s_ashr_i32 s44, s33, 11
	v_cndmask_b32_e32 v156, v240, v156, vcc
	v_lshlrev_b32_e32 v156, 2, v156
	s_lshl_b32 s19, s41, 1
	s_mov_b64 s[2:3], -1
	s_waitcnt vmcnt(0)
	v_mov_b32_e32 v196, v175
	v_mov_b32_e32 v197, v176
	v_mov_b32_e32 v175, v177
	v_pk_add_f32 v[174:175], v[196:197], v[174:175]
	v_mov_b32_e32 v176, v179
	v_mov_b32_e32 v177, v180
	v_mov_b32_e32 v179, v181
	v_pk_add_f32 v[176:177], v[176:177], v[178:179]
	v_mov_b32_e32 v179, v174
	v_mov_b32_e32 v178, v176
	v_mov_b32_e32 v174, v177
	v_pk_add_f32 v[174:175], v[178:179], v[174:175]
	ds_bpermute_b32 v177, v152, v175
	ds_bpermute_b32 v176, v152, v174
	s_waitcnt lgkmcnt(0)
	v_pk_add_f32 v[174:175], v[174:175], v[176:177]
	ds_bpermute_b32 v177, v156, v175
	ds_bpermute_b32 v176, v156, v174
	s_waitcnt lgkmcnt(0)
	v_pk_add_f32 v[174:175], v[174:175], v[176:177]
	s_nop 0
	v_pk_fma_f32 v[178:179], v[174:175], s[0:1], v[236:237] op_sel_hi:[1,0,0]
	v_mov_b32_e32 v174, v189
	v_mov_b32_e32 v175, v190
	v_mov_b32_e32 v189, v191
	v_mov_b32_e32 v176, v193
	v_mov_b32_e32 v177, v194
	v_mov_b32_e32 v193, v195
	v_pk_add_f32 v[174:175], v[174:175], v[188:189]
	v_pk_add_f32 v[176:177], v[176:177], v[192:193]
	v_mov_b32_e32 v189, v174
	v_mov_b32_e32 v188, v176
	v_mov_b32_e32 v174, v177
	v_pk_add_f32 v[174:175], v[188:189], v[174:175]
	v_mov_b32_e32 v188, v137
	v_mov_b32_e32 v189, v138
	v_mov_b32_e32 v137, v139
	v_mov_b32_e32 v138, v141
	v_mov_b32_e32 v139, v142
	v_mov_b32_e32 v141, v143
	v_pk_add_f32 v[136:137], v[188:189], v[136:137]
	v_pk_add_f32 v[138:139], v[138:139], v[140:141]
	v_mov_b32_e32 v141, v136
	v_mov_b32_e32 v140, v138
	v_mov_b32_e32 v136, v139
	v_pk_add_f32 v[136:137], v[140:141], v[136:137]
	v_mov_b32_e32 v140, v133
	v_mov_b32_e32 v141, v134
	v_mov_b32_e32 v133, v135
	v_mov_b32_e32 v134, v129
	v_mov_b32_e32 v135, v130
	v_mov_b32_e32 v129, v131
	v_pk_add_f32 v[132:133], v[140:141], v[132:133]
	v_pk_add_f32 v[128:129], v[134:135], v[128:129]
	v_mov_b32_e32 v131, v132
	v_mov_b32_e32 v130, v128
	v_mov_b32_e32 v132, v129
	v_pk_add_f32 v[128:129], v[130:131], v[132:133]
	ds_bpermute_b32 v177, v152, v175
	ds_bpermute_b32 v176, v152, v174
	ds_bpermute_b32 v139, v152, v137
	ds_bpermute_b32 v138, v152, v136
	ds_bpermute_b32 v131, v152, v129
	ds_bpermute_b32 v130, v152, v128
	v_mul_f32_e32 v157, 0x4b800000, v179
	v_cmp_gt_f32_e32 vcc, s96, v179
	s_and_b32 s0, s33, 0x7c0
	s_waitcnt lgkmcnt(4)
	v_pk_add_f32 v[174:175], v[174:175], v[176:177]
	v_cndmask_b32_e32 v157, v179, v157, vcc
	v_rsq_f32_e32 v157, v157
	s_waitcnt lgkmcnt(2)
	v_pk_add_f32 v[136:137], v[136:137], v[138:139]
	s_waitcnt lgkmcnt(0)
	v_pk_add_f32 v[128:129], v[128:129], v[130:131]
	v_or_b32_e32 v135, s0, v184
	s_lshl_b32 s0, s44, 7
	s_bfe_u32 s1, s33, 0x50006
	ds_bpermute_b32 v177, v156, v175
	ds_bpermute_b32 v176, v156, v174
	ds_bpermute_b32 v139, v156, v137
	ds_bpermute_b32 v138, v156, v136
	ds_bpermute_b32 v131, v156, v129
	ds_bpermute_b32 v130, v156, v128
	s_or_b32 s43, s0, s1
	v_mul_f32_e32 v158, 0x45800000, v157
	s_add_i32 s43, s43, 0x1fffd00
	v_cndmask_b32_e32 v180, v157, v158, vcc
	s_cmp_gt_i32 s41, 11
	v_pk_mul_f32 v[126:127], v[126:127], v[180:181] op_sel_hi:[1,0]
	v_pk_mul_f32 v[124:125], v[124:125], v[180:181] op_sel_hi:[1,0]
	v_pk_mul_f32 v[132:133], v[122:123], v[180:181] op_sel_hi:[1,0]
	v_pk_mul_f32 v[122:123], v[120:121], v[180:181] op_sel_hi:[1,0]
	s_cselect_b64 s[0:1], -1, 0
	v_xor_b32_e32 v134, 1, v240
	v_cmp_gt_f32_e64 s[8:9], s96, v178
	v_cvt_pk_bf16_f32 v120, v124, v125
	v_cvt_pk_bf16_f32 v121, v126, v127
	v_cvt_pk_bf16_f32 v122, v122, v123
	v_cvt_pk_bf16_f32 v123, v132, v133
	s_and_b64 vcc, exec, s[0:1]
	v_cmp_lt_i32_e64 s[10:11], v134, v186
	s_cbranch_vccz .LBB0_125
	s_nop 0
	v_cndmask_b32_e64 v124, v240, v134, s[10:11]
	v_lshlrev_b32_e32 v124, 2, v124
	s_nop 1
	v_mov_b32_dpp v125, v120 quad_perm:[1,0,3,2] row_mask:0xf bank_mask:0xf
	v_mov_b32_dpp v126, v121 quad_perm:[1,0,3,2] row_mask:0xf bank_mask:0xf
	v_mov_b32_dpp v127, v122 quad_perm:[1,0,3,2] row_mask:0xf bank_mask:0xf
	v_mov_b32_dpp v132, v123 quad_perm:[1,0,3,2] row_mask:0xf bank_mask:0xf
	s_lshl_b32 s12, s41, 13
	s_cmp_gt_u32 s19, 27
	s_cbranch_scc0 .LBB0_122
	s_lshl_b32 s2, s44, 14
	s_add_i32 s3, s12, s40
	s_add_i32 s3, s3, s2
	v_or_b32_e32 v124, s3, v135
	s_mov_b64 s[2:3], s[68:69]
	s_cbranch_execz .LBB0_123
	s_branch .LBB0_124

;     __device__ __forceinline__ void operator()(const f32x4 (&acc)[2][2][4][2], const Unit& u, int wr, int wc, int fr, int fq) const {
;     ...
;                 for (int bj = 0; bj < 2; ++bj) {
;                     const int tn = 2 * u.pn + bj;
;                     const int cw = 32 * wc + 8 * fq;
;                     const f32x4 v0 = acc[ai][bj][m][0] * rstd, v1 = acc[ai][bj][m][1] * rstd;
;                     u32x4 w; w.x = ::cvt_pk_bf16(v0[0], v0[1]); w.y = ::cvt_pk_bf16(v0[2], v0[3]); w.z = ::cvt_pk_bf16(v1[0], v1[1]); w.w = ::cvt_pk_bf16(v1[2], v1[3]);
;                     if (tn < 24) {
;                         bf16_t* dst;
;                         if (tn < 8) dst = z + (size_t)(tn >> 2) * ZS_KD + ((size_t)((b * 4 + (tn & 3)) * 2048 + s)) * 128 + cw;
;                         else if (tn < 16) dst = z + ZS_QN + (size_t)((tn - 8) >> 2) * (ZS_KN - ZS_QN) + ((size_t)((b * 8 + ((tn - 8) & 3) * 2 + (cw >> 6)) * 2048 + s)) * 64 + (cw & 63);
;                         else dst = z + ZS_GATE + (size_t)row * 1024 + (tn - 16) * 128 + cw;
;                         *(u32x4*)dst = w;
;                     } else {
;                         const unsigned ox = __shfl_xor(w.x, 1), oy = __shfl_xor(w.y, 1), oz = __shfl_xor(w.z, 1), ow = __shfl_xor(w.w, 1);
;                         const bool odd = fr & 1;
;                         const unsigned a0 = odd ? oz : w.x, a1 = odd ? ow : w.y;
;                         const unsigned b0 = odd ? w.z : ox, b1 = odd ? w.w : oy;
;                         const unsigned p0 = (a0 & 0xffffu) | (b0 << 16), p1 = (a0 >> 16) | (b0 & 0xffff0000u);
.LBB0_135:
	v_mov_b32_e32 v181, v180
	s_or_b32 s21, s19, 1
	v_mov_b32_e32 v120, v180
	v_mov_b32_e32 v121, v180
	v_pk_mul_f32 v[118:119], v[118:119], v[120:121]
	v_pk_mul_f32 v[116:117], v[116:117], v[180:181]
	v_pk_mul_f32 v[120:121], v[114:115], v[120:121]
	v_pk_mul_f32 v[114:115], v[112:113], v[180:181]
	s_cmp_gt_i32 s21, 23
	v_cvt_pk_bf16_f32 v112, v116, v117
	v_cvt_pk_bf16_f32 v113, v118, v119
	v_cvt_pk_bf16_f32 v114, v114, v115
	v_cvt_pk_bf16_f32 v115, v120, v121
	s_cselect_b64 s[2:3], -1, 0
	s_cmp_lt_i32 s21, 24
	s_mov_b64 s[10:11], -1
	s_cbranch_scc1 .LBB0_141
	v_cmp_lt_i32_e32 vcc, v134, v186
	s_lshl_b32 s46, s21, 12
	s_cmp_lt_u32 s19, 28
	v_cndmask_b32_e32 v116, v240, v134, vcc
	v_lshlrev_b32_e32 v116, 2, v116
	s_nop 1
	v_mov_b32_dpp v117, v112 quad_perm:[1,0,3,2] row_mask:0xf bank_mask:0xf
	v_mov_b32_dpp v118, v113 quad_perm:[1,0,3,2] row_mask:0xf bank_mask:0xf
	v_mov_b32_dpp v119, v114 quad_perm:[1,0,3,2] row_mask:0xf bank_mask:0xf
	v_mov_b32_dpp v120, v115 quad_perm:[1,0,3,2] row_mask:0xf bank_mask:0xf
	s_cbranch_scc1 .LBB0_138
	s_lshl_b32 s10, s44, 14
	s_add_i32 s11, s46, s40
	s_add_i32 s11, s11, s10
	v_or_b32_e32 v116, s11, v135
	s_mov_b64 s[10:11], s[68:69]
	s_cbranch_execz .LBB0_139
	s_branch .LBB0_140

;     __device__ __forceinline__ void operator()(const f32x4 (&acc)[2][2][4][2], const Unit& u, int wr, int wc, int fr, int fq) const {
;     ...
;             for (int m = 0; m < 4; ++m) {
;                 float s = (part[ai][m][0] + part[ai][m][1]) + (part[ai][m][2] + part[ai][m][3]);
;                 s += __shfl_xor(s, 16); s += __shfl_xor(s, 32);
;                 rstdv[ai][m] = rsqrtf(s * (1.0f / 1024.0f) + RMS_EPS);
;             }
; #pragma unroll
;         for (int ai = 0; ai < 2; ++ai)
; #pragma unroll
;             for (int m = 0; m < 4; ++m) {
;                 const int row = u.pm * BM + ai * HALF + wr * 64 + m * 16 + fr;
;                 const float rstd = rstdv[ai][m];
;                 const int b = row >> 11, s = row & 2047;
; #pragma unroll
;                 for (int bj = 0; bj < 2; ++bj) {
;                     const int tn = 2 * u.pn + bj;
;                     const int cw = 32 * wc + 8 * fq;
;                     const f32x4 v0 = acc[ai][bj][m][0] * rstd, v1 = acc[ai][bj][m][1] * rstd;
;                     u32x4 w; w.x = ::cvt_pk_bf16(v0[0], v0[1]); w.y = ::cvt_pk_bf16(v0[2], v0[3]); w.z = ::cvt_pk_bf16(v1[0], v1[1]); w.w = ::cvt_pk_bf16(v1[2], v1[3]);
;                     if (tn < 24) {
;                         bf16_t* dst;
;                         if (tn < 8) dst = z + (size_t)(tn >> 2) * ZS_KD + ((size_t)((b * 4 + (tn & 3)) * 2048 + s)) * 128 + cw;
;                         else if (tn < 16) dst = z + ZS_QN + (size_t)((tn - 8) >> 2) * (ZS_KN - ZS_QN) + ((size_t)((b * 8 + ((tn - 8) & 3) * 2 + (cw >> 6)) * 2048 + s)) * 64 + (cw & 63);
;                         else dst = z + ZS_GATE + (size_t)row * 1024 + (tn - 16) * 128 + cw;
;                         *(u32x4*)dst = w;
;                     } else {
;                         const unsigned ox = __shfl_xor(w.x, 1), oy = __shfl_xor(w.y, 1), oz = __shfl_xor(w.z, 1), ow = __shfl_xor(w.w, 1);
;                         const bool odd = fr & 1;
;                         const unsigned a0 = odd ? oz : w.x, a1 = odd ? ow : w.y;
;                         const unsigned b0 = odd ? w.z : ox, b1 = odd ? w.w : oy;
;                         const unsigned p0 = (a0 & 0xffffu) | (b0 << 16), p1 = (a0 >> 16) | (b0 & 0xffff0000u);
.LBB0_151:
	s_nop 1
	v_mul_f32_e32 v112, 0x4b800000, v178
	v_cndmask_b32_e64 v112, v178, v112, s[8:9]
	v_rsq_f32_e32 v112, v112
	v_bitop3_b32 v115, v124, 30, 16 bitop3:0xc8
	s_andn2_b64 vcc, exec, s[0:1]
	v_mul_f32_e32 v113, 0x45800000, v112
	v_cndmask_b32_e64 v112, v112, v113, s[8:9]
	v_pk_mul_f32 v[108:109], v[108:109], v[112:113] op_sel_hi:[1,0]
	v_pk_mul_f32 v[110:111], v[110:111], v[112:113] op_sel_hi:[1,0]
	v_pk_mul_f32 v[116:117], v[106:107], v[112:113] op_sel_hi:[1,0]
	v_pk_mul_f32 v[106:107], v[104:105], v[112:113] op_sel_hi:[1,0]
	v_cvt_pk_bf16_f32 v104, v108, v109
	v_cndmask_b32_e64 v108, 0, 1, s[0:1]
	v_cvt_pk_bf16_f32 v105, v110, v111
	v_cvt_pk_bf16_f32 v106, v106, v107
	v_cvt_pk_bf16_f32 v107, v116, v117
	v_cmp_ne_u32_e64 s[8:9], 1, v108
	s_mov_b64 s[0:1], -1
	s_cbranch_vccnz .LBB0_157
	v_cmp_lt_i32_e32 vcc, v134, v186
	s_lshl_b32 s12, s41, 13
	s_cmp_lt_u32 s19, 28
	v_cndmask_b32_e32 v108, v240, v134, vcc
	v_lshlrev_b32_e32 v108, 2, v108
	s_nop 1
	v_mov_b32_dpp v109, v104 quad_perm:[1,0,3,2] row_mask:0xf bank_mask:0xf
	v_mov_b32_dpp v110, v105 quad_perm:[1,0,3,2] row_mask:0xf bank_mask:0xf
	v_mov_b32_dpp v111, v106 quad_perm:[1,0,3,2] row_mask:0xf bank_mask:0xf
	v_mov_b32_dpp v113, v107 quad_perm:[1,0,3,2] row_mask:0xf bank_mask:0xf
	s_cbranch_scc1 .LBB0_154
	s_lshl_b32 s0, s44, 14
	s_add_i32 s1, s12, s40
	s_add_i32 s1, s1, s0
	v_or_b32_e32 v108, s1, v135
	s_mov_b64 s[0:1], s[68:69]
	s_cbranch_execz .LBB0_155
	s_branch .LBB0_156

;     __device__ __forceinline__ void operator()(const f32x4 (&acc)[2][2][4][2], const Unit& u, int wr, int wc, int fr, int fq) const {
;     ...
;                 for (int bj = 0; bj < 2; ++bj) {
;                     const int tn = 2 * u.pn + bj;
;                     const int cw = 32 * wc + 8 * fq;
;                     const f32x4 v0 = acc[ai][bj][m][0] * rstd, v1 = acc[ai][bj][m][1] * rstd;
;                     u32x4 w; w.x = ::cvt_pk_bf16(v0[0], v0[1]); w.y = ::cvt_pk_bf16(v0[2], v0[3]); w.z = ::cvt_pk_bf16(v1[0], v1[1]); w.w = ::cvt_pk_bf16(v1[2], v1[3]);
;                     if (tn < 24) {
;                         bf16_t* dst;
;                         if (tn < 8) dst = z + (size_t)(tn >> 2) * ZS_KD + ((size_t)((b * 4 + (tn & 3)) * 2048 + s)) * 128 + cw;
;                         else if (tn < 16) dst = z + ZS_QN + (size_t)((tn - 8) >> 2) * (ZS_KN - ZS_QN) + ((size_t)((b * 8 + ((tn - 8) & 3) * 2 + (cw >> 6)) * 2048 + s)) * 64 + (cw & 63);
;                         else dst = z + ZS_GATE + (size_t)row * 1024 + (tn - 16) * 128 + cw;
;                         *(u32x4*)dst = w;
;                     } else {
;                         const unsigned ox = __shfl_xor(w.x, 1), oy = __shfl_xor(w.y, 1), oz = __shfl_xor(w.z, 1), ow = __shfl_xor(w.w, 1);
;                         const bool odd = fr & 1;
;                         const unsigned a0 = odd ? oz : w.x, a1 = odd ? ow : w.y;
;                         const unsigned b0 = odd ? w.z : ox, b1 = odd ? w.w : oy;
;                         const unsigned p0 = (a0 & 0xffffu) | (b0 << 16), p1 = (a0 >> 16) | (b0 & 0xffff0000u);
.LBB0_167:
	v_mov_b32_e32 v113, v112
	s_nop 0
	v_mov_b32_e32 v104, v112
	v_mov_b32_e32 v105, v112
	v_pk_mul_f32 v[100:101], v[100:101], v[112:113]
	v_pk_mul_f32 v[102:103], v[102:103], v[104:105]
	v_pk_mul_f32 v[104:105], v[98:99], v[104:105]
	v_pk_mul_f32 v[98:99], v[96:97], v[112:113]
	v_cvt_pk_bf16_f32 v96, v100, v101
	v_cndmask_b32_e64 v100, 0, 1, s[2:3]
	v_cvt_pk_bf16_f32 v97, v102, v103
	v_cvt_pk_bf16_f32 v98, v98, v99
	v_cvt_pk_bf16_f32 v99, v104, v105
	v_cmp_ne_u32_e64 s[10:11], 1, v100
	s_andn2_b64 vcc, exec, s[2:3]
	s_mov_b64 s[0:1], -1
	s_cbranch_vccnz .LBB0_173
	v_cmp_lt_i32_e32 vcc, v134, v186
	s_lshl_b32 s12, s21, 12
	s_cmp_lt_u32 s19, 28
	v_cndmask_b32_e32 v100, v240, v134, vcc
	v_lshlrev_b32_e32 v100, 2, v100
	s_nop 1
	v_mov_b32_dpp v101, v96 quad_perm:[1,0,3,2] row_mask:0xf bank_mask:0xf
	v_mov_b32_dpp v102, v97 quad_perm:[1,0,3,2] row_mask:0xf bank_mask:0xf
	v_mov_b32_dpp v103, v98 quad_perm:[1,0,3,2] row_mask:0xf bank_mask:0xf
	v_mov_b32_dpp v104, v99 quad_perm:[1,0,3,2] row_mask:0xf bank_mask:0xf
	s_cbranch_scc1 .LBB0_170
	s_lshl_b32 s0, s44, 14
	s_add_i32 s1, s12, s40
	s_add_i32 s1, s1, s0
	v_or_b32_e32 v100, s1, v135
	s_mov_b64 s[0:1], s[68:69]
	s_cbranch_execz .LBB0_171
	s_branch .LBB0_172

;     __device__ __forceinline__ void operator()(const f32x4 (&acc)[2][2][4][2], const Unit& u, int wr, int wc, int fr, int fq) const {
;     ...
;             for (int m = 0; m < 4; ++m) {
;                 float s = (part[ai][m][0] + part[ai][m][1]) + (part[ai][m][2] + part[ai][m][3]);
;                 s += __shfl_xor(s, 16); s += __shfl_xor(s, 32);
;                 rstdv[ai][m] = rsqrtf(s * (1.0f / 1024.0f) + RMS_EPS);
;             }
; #pragma unroll
;         for (int ai = 0; ai < 2; ++ai)
; #pragma unroll
;             for (int m = 0; m < 4; ++m) {
;                 const int row = u.pm * BM + ai * HALF + wr * 64 + m * 16 + fr;
;                 const float rstd = rstdv[ai][m];
;                 const int b = row >> 11, s = row & 2047;
; #pragma unroll
;                 for (int bj = 0; bj < 2; ++bj) {
;                     const int tn = 2 * u.pn + bj;
;                     const int cw = 32 * wc + 8 * fq;
;                     const f32x4 v0 = acc[ai][bj][m][0] * rstd, v1 = acc[ai][bj][m][1] * rstd;
;                     u32x4 w; w.x = ::cvt_pk_bf16(v0[0], v0[1]); w.y = ::cvt_pk_bf16(v0[2], v0[3]); w.z = ::cvt_pk_bf16(v1[0], v1[1]); w.w = ::cvt_pk_bf16(v1[2], v1[3]);
;                     if (tn < 24) {
;                         bf16_t* dst;
;                         if (tn < 8) dst = z + (size_t)(tn >> 2) * ZS_KD + ((size_t)((b * 4 + (tn & 3)) * 2048 + s)) * 128 + cw;
;                         else if (tn < 16) dst = z + ZS_QN + (size_t)((tn - 8) >> 2) * (ZS_KN - ZS_QN) + ((size_t)((b * 8 + ((tn - 8) & 3) * 2 + (cw >> 6)) * 2048 + s)) * 64 + (cw & 63);
;                         else dst = z + ZS_GATE + (size_t)row * 1024 + (tn - 16) * 128 + cw;
;                         *(u32x4*)dst = w;
;                     } else {
;                         const unsigned ox = __shfl_xor(w.x, 1), oy = __shfl_xor(w.y, 1), oz = __shfl_xor(w.z, 1), ow = __shfl_xor(w.w, 1);
;                         const bool odd = fr & 1;
;                         const unsigned a0 = odd ? oz : w.x, a1 = odd ? ow : w.y;
;                         const unsigned b0 = odd ? w.z : ox, b1 = odd ? w.w : oy;
;                         const unsigned p0 = (a0 & 0xffffu) | (b0 << 16), p1 = (a0 >> 16) | (b0 & 0xffff0000u);
.LBB0_183:
	s_waitcnt lgkmcnt(4)
	s_nop 0
	v_pk_add_f32 v[96:97], v[174:175], v[176:177]
	s_mov_b32 s0, 0x3a800000
	v_pk_fma_f32 v[96:97], v[96:97], s[0:1], v[236:237] op_sel_hi:[1,0,0]
	v_bitop3_b32 v100, v124, 46, 32 bitop3:0xc8
	v_mul_f32_e32 v98, 0x4b800000, v97
	v_cmp_gt_f32_e32 vcc, s96, v97
	v_cmp_gt_f32_e64 s[12:13], s96, v96
	s_mov_b64 s[0:1], -1
	v_cndmask_b32_e32 v97, v97, v98, vcc
	v_rsq_f32_e32 v97, v97
	s_nop 0
	v_mul_f32_e32 v98, 0x45800000, v97
	v_cndmask_b32_e32 v98, v97, v98, vcc
	v_pk_mul_f32 v[94:95], v[94:95], v[98:99] op_sel_hi:[1,0]
	v_pk_mul_f32 v[92:93], v[92:93], v[98:99] op_sel_hi:[1,0]
	v_pk_mul_f32 v[102:103], v[90:91], v[98:99] op_sel_hi:[1,0]
	v_pk_mul_f32 v[90:91], v[88:89], v[98:99] op_sel_hi:[1,0]
	v_cvt_pk_bf16_f32 v88, v92, v93
	v_cvt_pk_bf16_f32 v89, v94, v95
	v_cvt_pk_bf16_f32 v90, v90, v91
	v_cvt_pk_bf16_f32 v91, v102, v103
	s_and_b64 vcc, exec, s[8:9]
	s_cbranch_vccnz .LBB0_189
	v_cmp_lt_i32_e32 vcc, v134, v186
	s_lshl_b32 s46, s41, 13
	s_cmp_lt_u32 s19, 28
	v_cndmask_b32_e32 v92, v240, v134, vcc
	v_lshlrev_b32_e32 v92, 2, v92
	s_nop 1
	v_mov_b32_dpp v93, v88 quad_perm:[1,0,3,2] row_mask:0xf bank_mask:0xf
	v_mov_b32_dpp v94, v89 quad_perm:[1,0,3,2] row_mask:0xf bank_mask:0xf
	v_mov_b32_dpp v95, v90 quad_perm:[1,0,3,2] row_mask:0xf bank_mask:0xf
	v_mov_b32_dpp v97, v91 quad_perm:[1,0,3,2] row_mask:0xf bank_mask:0xf
	s_cbranch_scc1 .LBB0_186
	s_lshl_b32 s0, s44, 14
	s_add_i32 s1, s46, s40
	s_add_i32 s1, s1, s0
	v_or_b32_e32 v92, s1, v135
	s_mov_b64 s[0:1], s[68:69]
	s_cbranch_execz .LBB0_187
	s_branch .LBB0_188

;     __device__ __forceinline__ void operator()(const f32x4 (&acc)[2][2][4][2], const Unit& u, int wr, int wc, int fr, int fq) const {
;     ...
;                 for (int bj = 0; bj < 2; ++bj) {
;                     const int tn = 2 * u.pn + bj;
;                     const int cw = 32 * wc + 8 * fq;
;                     const f32x4 v0 = acc[ai][bj][m][0] * rstd, v1 = acc[ai][bj][m][1] * rstd;
;                     u32x4 w; w.x = ::cvt_pk_bf16(v0[0], v0[1]); w.y = ::cvt_pk_bf16(v0[2], v0[3]); w.z = ::cvt_pk_bf16(v1[0], v1[1]); w.w = ::cvt_pk_bf16(v1[2], v1[3]);
;                     if (tn < 24) {
;                         bf16_t* dst;
;                         if (tn < 8) dst = z + (size_t)(tn >> 2) * ZS_KD + ((size_t)((b * 4 + (tn & 3)) * 2048 + s)) * 128 + cw;
;                         else if (tn < 16) dst = z + ZS_QN + (size_t)((tn - 8) >> 2) * (ZS_KN - ZS_QN) + ((size_t)((b * 8 + ((tn - 8) & 3) * 2 + (cw >> 6)) * 2048 + s)) * 64 + (cw & 63);
;                         else dst = z + ZS_GATE + (size_t)row * 1024 + (tn - 16) * 128 + cw;
;                         *(u32x4*)dst = w;
;                     } else {
;                         const unsigned ox = __shfl_xor(w.x, 1), oy = __shfl_xor(w.y, 1), oz = __shfl_xor(w.z, 1), ow = __shfl_xor(w.w, 1);
;                         const bool odd = fr & 1;
;                         const unsigned a0 = odd ? oz : w.x, a1 = odd ? ow : w.y;
;                         const unsigned b0 = odd ? w.z : ox, b1 = odd ? w.w : oy;
;                         const unsigned p0 = (a0 & 0xffffu) | (b0 << 16), p1 = (a0 >> 16) | (b0 & 0xffff0000u);
.LBB0_199:
	v_mov_b32_e32 v99, v98
	s_nop 0
	v_mov_b32_e32 v88, v98
	v_mov_b32_e32 v89, v98
	v_pk_mul_f32 v[86:87], v[86:87], v[88:89]
	v_pk_mul_f32 v[84:85], v[84:85], v[98:99]
	v_pk_mul_f32 v[88:89], v[82:83], v[88:89]
	v_pk_mul_f32 v[82:83], v[80:81], v[98:99]
	v_cvt_pk_bf16_f32 v80, v84, v85
	v_cvt_pk_bf16_f32 v81, v86, v87
	v_cvt_pk_bf16_f32 v82, v82, v83
	v_cvt_pk_bf16_f32 v83, v88, v89
	s_and_b64 vcc, exec, s[10:11]
	s_mov_b64 s[0:1], -1
	s_cbranch_vccnz .LBB0_205
	v_cmp_lt_i32_e32 vcc, v134, v186
	s_lshl_b32 s46, s21, 12
	s_cmp_lt_u32 s19, 28
	v_cndmask_b32_e32 v84, v240, v134, vcc
	v_lshlrev_b32_e32 v84, 2, v84
	s_nop 1
	v_mov_b32_dpp v85, v80 quad_perm:[1,0,3,2] row_mask:0xf bank_mask:0xf
	v_mov_b32_dpp v86, v81 quad_perm:[1,0,3,2] row_mask:0xf bank_mask:0xf
	v_mov_b32_dpp v87, v82 quad_perm:[1,0,3,2] row_mask:0xf bank_mask:0xf
	v_mov_b32_dpp v88, v83 quad_perm:[1,0,3,2] row_mask:0xf bank_mask:0xf
	s_cbranch_scc1 .LBB0_202
	s_lshl_b32 s0, s44, 14
	s_add_i32 s1, s46, s40
	s_add_i32 s1, s1, s0
	v_or_b32_e32 v84, s1, v135
	s_mov_b64 s[0:1], s[68:69]
	s_cbranch_execz .LBB0_203
	s_branch .LBB0_204

;     __device__ __forceinline__ void operator()(const f32x4 (&acc)[2][2][4][2], const Unit& u, int wr, int wc, int fr, int fq) const {
;     ...
;             for (int m = 0; m < 4; ++m) {
;                 float s = (part[ai][m][0] + part[ai][m][1]) + (part[ai][m][2] + part[ai][m][3]);
;                 s += __shfl_xor(s, 16); s += __shfl_xor(s, 32);
;                 rstdv[ai][m] = rsqrtf(s * (1.0f / 1024.0f) + RMS_EPS);
;             }
; #pragma unroll
;         for (int ai = 0; ai < 2; ++ai)
; #pragma unroll
;             for (int m = 0; m < 4; ++m) {
;                 const int row = u.pm * BM + ai * HALF + wr * 64 + m * 16 + fr;
;                 const float rstd = rstdv[ai][m];
;                 const int b = row >> 11, s = row & 2047;
; #pragma unroll
;                 for (int bj = 0; bj < 2; ++bj) {
;                     const int tn = 2 * u.pn + bj;
;                     const int cw = 32 * wc + 8 * fq;
;                     const f32x4 v0 = acc[ai][bj][m][0] * rstd, v1 = acc[ai][bj][m][1] * rstd;
;                     u32x4 w; w.x = ::cvt_pk_bf16(v0[0], v0[1]); w.y = ::cvt_pk_bf16(v0[2], v0[3]); w.z = ::cvt_pk_bf16(v1[0], v1[1]); w.w = ::cvt_pk_bf16(v1[2], v1[3]);
;                     if (tn < 24) {
;                         bf16_t* dst;
;                         if (tn < 8) dst = z + (size_t)(tn >> 2) * ZS_KD + ((size_t)((b * 4 + (tn & 3)) * 2048 + s)) * 128 + cw;
;                         else if (tn < 16) dst = z + ZS_QN + (size_t)((tn - 8) >> 2) * (ZS_KN - ZS_QN) + ((size_t)((b * 8 + ((tn - 8) & 3) * 2 + (cw >> 6)) * 2048 + s)) * 64 + (cw & 63);
;                         else dst = z + ZS_GATE + (size_t)row * 1024 + (tn - 16) * 128 + cw;
;                         *(u32x4*)dst = w;
;                     } else {
;                         const unsigned ox = __shfl_xor(w.x, 1), oy = __shfl_xor(w.y, 1), oz = __shfl_xor(w.z, 1), ow = __shfl_xor(w.w, 1);
;                         const bool odd = fr & 1;
;                         const unsigned a0 = odd ? oz : w.x, a1 = odd ? ow : w.y;
;                         const unsigned b0 = odd ? w.z : ox, b1 = odd ? w.w : oy;
;                         const unsigned p0 = (a0 & 0xffffu) | (b0 << 16), p1 = (a0 >> 16) | (b0 & 0xffff0000u);
.LBB0_215:
	s_nop 1
	v_mul_f32_e32 v80, 0x4b800000, v96
	v_cndmask_b32_e64 v80, v96, v80, s[12:13]
	v_rsq_f32_e32 v80, v80
	v_bitop3_b32 v83, v124, 62, 48 bitop3:0xc8
	s_and_b64 vcc, exec, s[8:9]
	s_mov_b64 s[0:1], -1
	v_mul_f32_e32 v81, 0x45800000, v80
	v_cndmask_b32_e64 v80, v80, v81, s[12:13]
	v_pk_mul_f32 v[78:79], v[78:79], v[80:81] op_sel_hi:[1,0]
	v_pk_mul_f32 v[76:77], v[76:77], v[80:81] op_sel_hi:[1,0]
	v_pk_mul_f32 v[84:85], v[74:75], v[80:81] op_sel_hi:[1,0]
	v_pk_mul_f32 v[74:75], v[72:73], v[80:81] op_sel_hi:[1,0]
	v_cvt_pk_bf16_f32 v72, v76, v77
	v_cvt_pk_bf16_f32 v73, v78, v79
	v_cvt_pk_bf16_f32 v74, v74, v75
	v_cvt_pk_bf16_f32 v75, v84, v85
	s_cbranch_vccnz .LBB0_221
	v_cmp_lt_i32_e32 vcc, v134, v186
	s_lshl_b32 s12, s41, 13
	s_cmp_lt_u32 s19, 28
	v_cndmask_b32_e32 v76, v240, v134, vcc
	v_lshlrev_b32_e32 v76, 2, v76
	s_nop 1
	v_mov_b32_dpp v77, v72 quad_perm:[1,0,3,2] row_mask:0xf bank_mask:0xf
	v_mov_b32_dpp v78, v73 quad_perm:[1,0,3,2] row_mask:0xf bank_mask:0xf
	v_mov_b32_dpp v79, v74 quad_perm:[1,0,3,2] row_mask:0xf bank_mask:0xf
	v_mov_b32_dpp v81, v75 quad_perm:[1,0,3,2] row_mask:0xf bank_mask:0xf
	s_cbranch_scc1 .LBB0_218
	s_lshl_b32 s0, s44, 14
	s_add_i32 s1, s12, s40
	s_add_i32 s1, s1, s0
	v_or_b32_e32 v76, s1, v135
	s_mov_b64 s[0:1], s[68:69]
	s_cbranch_execz .LBB0_219
	s_branch .LBB0_220

;     __device__ __forceinline__ void operator()(const f32x4 (&acc)[2][2][4][2], const Unit& u, int wr, int wc, int fr, int fq) const {
;     ...
;                 for (int bj = 0; bj < 2; ++bj) {
;                     const int tn = 2 * u.pn + bj;
;                     const int cw = 32 * wc + 8 * fq;
;                     const f32x4 v0 = acc[ai][bj][m][0] * rstd, v1 = acc[ai][bj][m][1] * rstd;
;                     u32x4 w; w.x = ::cvt_pk_bf16(v0[0], v0[1]); w.y = ::cvt_pk_bf16(v0[2], v0[3]); w.z = ::cvt_pk_bf16(v1[0], v1[1]); w.w = ::cvt_pk_bf16(v1[2], v1[3]);
;                     if (tn < 24) {
;                         bf16_t* dst;
;                         if (tn < 8) dst = z + (size_t)(tn >> 2) * ZS_KD + ((size_t)((b * 4 + (tn & 3)) * 2048 + s)) * 128 + cw;
;                         else if (tn < 16) dst = z + ZS_QN + (size_t)((tn - 8) >> 2) * (ZS_KN - ZS_QN) + ((size_t)((b * 8 + ((tn - 8) & 3) * 2 + (cw >> 6)) * 2048 + s)) * 64 + (cw & 63);
;                         else dst = z + ZS_GATE + (size_t)row * 1024 + (tn - 16) * 128 + cw;
;                         *(u32x4*)dst = w;
;                     } else {
;                         const unsigned ox = __shfl_xor(w.x, 1), oy = __shfl_xor(w.y, 1), oz = __shfl_xor(w.z, 1), ow = __shfl_xor(w.w, 1);
;                         const bool odd = fr & 1;
;                         const unsigned a0 = odd ? oz : w.x, a1 = odd ? ow : w.y;
;                         const unsigned b0 = odd ? w.z : ox, b1 = odd ? w.w : oy;
;                         const unsigned p0 = (a0 & 0xffffu) | (b0 << 16), p1 = (a0 >> 16) | (b0 & 0xffff0000u);
.LBB0_231:
	v_mov_b32_e32 v81, v80
	s_nop 0
	v_mov_b32_e32 v72, v80
	v_mov_b32_e32 v73, v80
	v_pk_mul_f32 v[70:71], v[70:71], v[72:73]
	v_pk_mul_f32 v[68:69], v[68:69], v[80:81]
	v_pk_mul_f32 v[72:73], v[66:67], v[72:73]
	v_pk_mul_f32 v[66:67], v[64:65], v[80:81]
	v_cvt_pk_bf16_f32 v64, v68, v69
	v_cvt_pk_bf16_f32 v65, v70, v71
	v_cvt_pk_bf16_f32 v66, v66, v67
	v_cvt_pk_bf16_f32 v67, v72, v73
	s_and_b64 vcc, exec, s[10:11]
	s_mov_b64 s[0:1], -1
	s_cbranch_vccnz .LBB0_237
	v_cmp_lt_i32_e32 vcc, v134, v186
	s_lshl_b32 s12, s21, 12
	s_cmp_lt_u32 s19, 28
	v_cndmask_b32_e32 v68, v240, v134, vcc
	v_lshlrev_b32_e32 v68, 2, v68
	s_nop 1
	v_mov_b32_dpp v69, v64 quad_perm:[1,0,3,2] row_mask:0xf bank_mask:0xf
	v_mov_b32_dpp v70, v65 quad_perm:[1,0,3,2] row_mask:0xf bank_mask:0xf
	v_mov_b32_dpp v71, v66 quad_perm:[1,0,3,2] row_mask:0xf bank_mask:0xf
	v_mov_b32_dpp v72, v67 quad_perm:[1,0,3,2] row_mask:0xf bank_mask:0xf
	s_cbranch_scc1 .LBB0_234
	s_lshl_b32 s0, s44, 14
	s_add_i32 s1, s12, s40
	s_add_i32 s1, s1, s0
	v_or_b32_e32 v68, s1, v135
	s_mov_b64 s[0:1], s[68:69]
	s_cbranch_execz .LBB0_235
	s_branch .LBB0_236

;     __device__ __forceinline__ void operator()(const f32x4 (&acc)[2][2][4][2], const Unit& u, int wr, int wc, int fr, int fq) const {
;     ...
;             for (int m = 0; m < 4; ++m) {
;                 float s = (part[ai][m][0] + part[ai][m][1]) + (part[ai][m][2] + part[ai][m][3]);
;                 s += __shfl_xor(s, 16); s += __shfl_xor(s, 32);
;                 rstdv[ai][m] = rsqrtf(s * (1.0f / 1024.0f) + RMS_EPS);
;             }
; #pragma unroll
;         for (int ai = 0; ai < 2; ++ai)
; #pragma unroll
;             for (int m = 0; m < 4; ++m) {
;                 const int row = u.pm * BM + ai * HALF + wr * 64 + m * 16 + fr;
;                 const float rstd = rstdv[ai][m];
;                 const int b = row >> 11, s = row & 2047;
; #pragma unroll
;                 for (int bj = 0; bj < 2; ++bj) {
;                     const int tn = 2 * u.pn + bj;
;                     const int cw = 32 * wc + 8 * fq;
;                     const f32x4 v0 = acc[ai][bj][m][0] * rstd, v1 = acc[ai][bj][m][1] * rstd;
;                     u32x4 w; w.x = ::cvt_pk_bf16(v0[0], v0[1]); w.y = ::cvt_pk_bf16(v0[2], v0[3]); w.z = ::cvt_pk_bf16(v1[0], v1[1]); w.w = ::cvt_pk_bf16(v1[2], v1[3]);
;                     if (tn < 24) {
;                         bf16_t* dst;
;                         if (tn < 8) dst = z + (size_t)(tn >> 2) * ZS_KD + ((size_t)((b * 4 + (tn & 3)) * 2048 + s)) * 128 + cw;
;                         else if (tn < 16) dst = z + ZS_QN + (size_t)((tn - 8) >> 2) * (ZS_KN - ZS_QN) + ((size_t)((b * 8 + ((tn - 8) & 3) * 2 + (cw >> 6)) * 2048 + s)) * 64 + (cw & 63);
;                         else dst = z + ZS_GATE + (size_t)row * 1024 + (tn - 16) * 128 + cw;
;                         *(u32x4*)dst = w;
;                     } else {
;                         const unsigned ox = __shfl_xor(w.x, 1), oy = __shfl_xor(w.y, 1), oz = __shfl_xor(w.z, 1), ow = __shfl_xor(w.w, 1);
;                         const bool odd = fr & 1;
;                         const unsigned a0 = odd ? oz : w.x, a1 = odd ? ow : w.y;
;                         const unsigned b0 = odd ? w.z : ox, b1 = odd ? w.w : oy;
;                         const unsigned p0 = (a0 & 0xffffu) | (b0 << 16), p1 = (a0 >> 16) | (b0 & 0xffff0000u);
.LBB0_247:
	s_waitcnt lgkmcnt(2)
	s_nop 0
	v_pk_add_f32 v[64:65], v[136:137], v[138:139]
	s_mov_b32 s0, 0x3a800000
	v_pk_fma_f32 v[64:65], v[64:65], s[0:1], v[236:237] op_sel_hi:[1,0,0]
	s_addk_i32 s33, 0x80
	v_mul_f32_e32 v66, 0x4b800000, v65
	v_cmp_gt_f32_e32 vcc, s96, v65
	s_ashr_i32 s44, s33, 11
	s_and_b32 s0, s33, 0x7c0
	v_cndmask_b32_e32 v65, v65, v66, vcc
	v_rsq_f32_e32 v65, v65
	s_bfe_u32 s1, s33, 0x50006
	v_cmp_gt_f32_e64 s[12:13], s96, v64
	v_mul_f32_e32 v66, 0x45800000, v65
	v_cndmask_b32_e32 v66, v65, v66, vcc
	v_or_b32_e32 v65, s0, v184
	s_lshl_b32 s0, s44, 7
	s_or_b32 s42, s0, s1
	v_pk_mul_f32 v[62:63], v[62:63], v[66:67] op_sel_hi:[1,0]
	v_pk_mul_f32 v[60:61], v[60:61], v[66:67] op_sel_hi:[1,0]
	v_pk_mul_f32 v[68:69], v[58:59], v[66:67] op_sel_hi:[1,0]
	v_pk_mul_f32 v[58:59], v[56:57], v[66:67] op_sel_hi:[1,0]
	s_add_i32 s42, s42, 0x1fffd00
	v_cvt_pk_bf16_f32 v56, v60, v61
	v_cvt_pk_bf16_f32 v57, v62, v63
	v_cvt_pk_bf16_f32 v58, v58, v59
	v_cvt_pk_bf16_f32 v59, v68, v69
	s_and_b64 vcc, exec, s[8:9]
	s_mov_b64 s[0:1], -1
	s_cbranch_vccnz .LBB0_253
	v_cmp_lt_i32_e32 vcc, v134, v186
	s_lshl_b32 s43, s41, 13
	s_cmp_lt_u32 s19, 28
	v_cndmask_b32_e32 v60, v240, v134, vcc
	v_lshlrev_b32_e32 v60, 2, v60
	s_nop 1
	v_mov_b32_dpp v61, v56 quad_perm:[1,0,3,2] row_mask:0xf bank_mask:0xf
	v_mov_b32_dpp v62, v57 quad_perm:[1,0,3,2] row_mask:0xf bank_mask:0xf
	v_mov_b32_dpp v63, v58 quad_perm:[1,0,3,2] row_mask:0xf bank_mask:0xf
	v_mov_b32_dpp v67, v59 quad_perm:[1,0,3,2] row_mask:0xf bank_mask:0xf
	s_cbranch_scc1 .LBB0_250
	s_lshl_b32 s0, s44, 14
	s_add_i32 s1, s43, s40
	s_add_i32 s1, s1, s0
	v_or_b32_e32 v60, s1, v65
	s_mov_b64 s[0:1], s[68:69]
	s_cbranch_execz .LBB0_251
	s_branch .LBB0_252

;     __device__ __forceinline__ void operator()(const f32x4 (&acc)[2][2][4][2], const Unit& u, int wr, int wc, int fr, int fq) const {
;     ...
;                 for (int bj = 0; bj < 2; ++bj) {
;                     const int tn = 2 * u.pn + bj;
;                     const int cw = 32 * wc + 8 * fq;
;                     const f32x4 v0 = acc[ai][bj][m][0] * rstd, v1 = acc[ai][bj][m][1] * rstd;
;                     u32x4 w; w.x = ::cvt_pk_bf16(v0[0], v0[1]); w.y = ::cvt_pk_bf16(v0[2], v0[3]); w.z = ::cvt_pk_bf16(v1[0], v1[1]); w.w = ::cvt_pk_bf16(v1[2], v1[3]);
;                     if (tn < 24) {
;                         bf16_t* dst;
;                         if (tn < 8) dst = z + (size_t)(tn >> 2) * ZS_KD + ((size_t)((b * 4 + (tn & 3)) * 2048 + s)) * 128 + cw;
;                         else if (tn < 16) dst = z + ZS_QN + (size_t)((tn - 8) >> 2) * (ZS_KN - ZS_QN) + ((size_t)((b * 8 + ((tn - 8) & 3) * 2 + (cw >> 6)) * 2048 + s)) * 64 + (cw & 63);
;                         else dst = z + ZS_GATE + (size_t)row * 1024 + (tn - 16) * 128 + cw;
;                         *(u32x4*)dst = w;
;                     } else {
;                         const unsigned ox = __shfl_xor(w.x, 1), oy = __shfl_xor(w.y, 1), oz = __shfl_xor(w.z, 1), ow = __shfl_xor(w.w, 1);
;                         const bool odd = fr & 1;
;                         const unsigned a0 = odd ? oz : w.x, a1 = odd ? ow : w.y;
;                         const unsigned b0 = odd ? w.z : ox, b1 = odd ? w.w : oy;
;                         const unsigned p0 = (a0 & 0xffffu) | (b0 << 16), p1 = (a0 >> 16) | (b0 & 0xffff0000u);
.LBB0_263:
	v_mov_b32_e32 v67, v66
	s_nop 0
	v_mov_b32_e32 v56, v66
	v_mov_b32_e32 v57, v66
	v_pk_mul_f32 v[54:55], v[54:55], v[56:57]
	v_pk_mul_f32 v[52:53], v[52:53], v[66:67]
	v_pk_mul_f32 v[56:57], v[50:51], v[56:57]
	v_pk_mul_f32 v[50:51], v[48:49], v[66:67]
	v_cvt_pk_bf16_f32 v48, v52, v53
	v_cvt_pk_bf16_f32 v49, v54, v55
	v_cvt_pk_bf16_f32 v50, v50, v51
	v_cvt_pk_bf16_f32 v51, v56, v57
	s_and_b64 vcc, exec, s[10:11]
	s_mov_b64 s[0:1], -1
	s_cbranch_vccnz .LBB0_269
	v_cmp_lt_i32_e32 vcc, v134, v186
	s_lshl_b32 s45, s21, 12
	s_cmp_lt_u32 s19, 28
	v_cndmask_b32_e32 v52, v240, v134, vcc
	v_lshlrev_b32_e32 v52, 2, v52
	s_nop 1
	v_mov_b32_dpp v53, v48 quad_perm:[1,0,3,2] row_mask:0xf bank_mask:0xf
	v_mov_b32_dpp v54, v49 quad_perm:[1,0,3,2] row_mask:0xf bank_mask:0xf
	v_mov_b32_dpp v55, v50 quad_perm:[1,0,3,2] row_mask:0xf bank_mask:0xf
	v_mov_b32_dpp v56, v51 quad_perm:[1,0,3,2] row_mask:0xf bank_mask:0xf
	s_cbranch_scc1 .LBB0_266
	s_lshl_b32 s0, s44, 14
	s_add_i32 s1, s45, s40
	s_add_i32 s1, s1, s0
	v_or_b32_e32 v52, s1, v65
	s_mov_b64 s[0:1], s[68:69]
	s_cbranch_execz .LBB0_267
	s_branch .LBB0_268

;     __device__ __forceinline__ void operator()(const f32x4 (&acc)[2][2][4][2], const Unit& u, int wr, int wc, int fr, int fq) const {
;     ...
;             for (int m = 0; m < 4; ++m) {
;                 float s = (part[ai][m][0] + part[ai][m][1]) + (part[ai][m][2] + part[ai][m][3]);
;                 s += __shfl_xor(s, 16); s += __shfl_xor(s, 32);
;                 rstdv[ai][m] = rsqrtf(s * (1.0f / 1024.0f) + RMS_EPS);
;             }
; #pragma unroll
;         for (int ai = 0; ai < 2; ++ai)
; #pragma unroll
;             for (int m = 0; m < 4; ++m) {
;                 const int row = u.pm * BM + ai * HALF + wr * 64 + m * 16 + fr;
;                 const float rstd = rstdv[ai][m];
;                 const int b = row >> 11, s = row & 2047;
; #pragma unroll
;                 for (int bj = 0; bj < 2; ++bj) {
;                     const int tn = 2 * u.pn + bj;
;                     const int cw = 32 * wc + 8 * fq;
;                     const f32x4 v0 = acc[ai][bj][m][0] * rstd, v1 = acc[ai][bj][m][1] * rstd;
;                     u32x4 w; w.x = ::cvt_pk_bf16(v0[0], v0[1]); w.y = ::cvt_pk_bf16(v0[2], v0[3]); w.z = ::cvt_pk_bf16(v1[0], v1[1]); w.w = ::cvt_pk_bf16(v1[2], v1[3]);
;                     if (tn < 24) {
;                         bf16_t* dst;
;                         if (tn < 8) dst = z + (size_t)(tn >> 2) * ZS_KD + ((size_t)((b * 4 + (tn & 3)) * 2048 + s)) * 128 + cw;
;                         else if (tn < 16) dst = z + ZS_QN + (size_t)((tn - 8) >> 2) * (ZS_KN - ZS_QN) + ((size_t)((b * 8 + ((tn - 8) & 3) * 2 + (cw >> 6)) * 2048 + s)) * 64 + (cw & 63);
;                         else dst = z + ZS_GATE + (size_t)row * 1024 + (tn - 16) * 128 + cw;
;                         *(u32x4*)dst = w;
;                     } else {
;                         const unsigned ox = __shfl_xor(w.x, 1), oy = __shfl_xor(w.y, 1), oz = __shfl_xor(w.z, 1), ow = __shfl_xor(w.w, 1);
;                         const bool odd = fr & 1;
;                         const unsigned a0 = odd ? oz : w.x, a1 = odd ? ow : w.y;
;                         const unsigned b0 = odd ? w.z : ox, b1 = odd ? w.w : oy;
;                         const unsigned p0 = (a0 & 0xffffu) | (b0 << 16), p1 = (a0 >> 16) | (b0 & 0xffff0000u);
.LBB0_279:
	s_nop 1
	v_mul_f32_e32 v48, 0x4b800000, v64
	v_cndmask_b32_e64 v48, v64, v48, s[12:13]
	v_rsq_f32_e32 v48, v48
	v_bitop3_b32 v51, v60, 30, 16 bitop3:0xc8
	s_and_b64 vcc, exec, s[8:9]
	s_mov_b64 s[0:1], -1
	v_mul_f32_e32 v49, 0x45800000, v48
	v_cndmask_b32_e64 v48, v48, v49, s[12:13]
	v_pk_mul_f32 v[46:47], v[46:47], v[48:49] op_sel_hi:[1,0]
	v_pk_mul_f32 v[44:45], v[44:45], v[48:49] op_sel_hi:[1,0]
	v_pk_mul_f32 v[52:53], v[42:43], v[48:49] op_sel_hi:[1,0]
	v_pk_mul_f32 v[42:43], v[40:41], v[48:49] op_sel_hi:[1,0]
	v_cvt_pk_bf16_f32 v40, v44, v45
	v_cvt_pk_bf16_f32 v41, v46, v47
	v_cvt_pk_bf16_f32 v42, v42, v43
	v_cvt_pk_bf16_f32 v43, v52, v53
	s_cbranch_vccnz .LBB0_285
	v_cmp_lt_i32_e32 vcc, v134, v186
	s_lshl_b32 s12, s41, 13
	s_cmp_lt_u32 s19, 28
	v_cndmask_b32_e32 v44, v240, v134, vcc
	v_lshlrev_b32_e32 v44, 2, v44
	s_nop 1
	v_mov_b32_dpp v45, v40 quad_perm:[1,0,3,2] row_mask:0xf bank_mask:0xf
	v_mov_b32_dpp v46, v41 quad_perm:[1,0,3,2] row_mask:0xf bank_mask:0xf
	v_mov_b32_dpp v47, v42 quad_perm:[1,0,3,2] row_mask:0xf bank_mask:0xf
	v_mov_b32_dpp v49, v43 quad_perm:[1,0,3,2] row_mask:0xf bank_mask:0xf
	s_cbranch_scc1 .LBB0_282
	s_lshl_b32 s0, s44, 14
	s_add_i32 s1, s12, s40
	s_add_i32 s1, s1, s0
	v_or_b32_e32 v44, s1, v65
	s_mov_b64 s[0:1], s[68:69]
	s_cbranch_execz .LBB0_283
	s_branch .LBB0_284

;     __device__ __forceinline__ void operator()(const f32x4 (&acc)[2][2][4][2], const Unit& u, int wr, int wc, int fr, int fq) const {
;     ...
;                 for (int bj = 0; bj < 2; ++bj) {
;                     const int tn = 2 * u.pn + bj;
;                     const int cw = 32 * wc + 8 * fq;
;                     const f32x4 v0 = acc[ai][bj][m][0] * rstd, v1 = acc[ai][bj][m][1] * rstd;
;                     u32x4 w; w.x = ::cvt_pk_bf16(v0[0], v0[1]); w.y = ::cvt_pk_bf16(v0[2], v0[3]); w.z = ::cvt_pk_bf16(v1[0], v1[1]); w.w = ::cvt_pk_bf16(v1[2], v1[3]);
;                     if (tn < 24) {
;                         bf16_t* dst;
;                         if (tn < 8) dst = z + (size_t)(tn >> 2) * ZS_KD + ((size_t)((b * 4 + (tn & 3)) * 2048 + s)) * 128 + cw;
;                         else if (tn < 16) dst = z + ZS_QN + (size_t)((tn - 8) >> 2) * (ZS_KN - ZS_QN) + ((size_t)((b * 8 + ((tn - 8) & 3) * 2 + (cw >> 6)) * 2048 + s)) * 64 + (cw & 63);
;                         else dst = z + ZS_GATE + (size_t)row * 1024 + (tn - 16) * 128 + cw;
;                         *(u32x4*)dst = w;
;                     } else {
;                         const unsigned ox = __shfl_xor(w.x, 1), oy = __shfl_xor(w.y, 1), oz = __shfl_xor(w.z, 1), ow = __shfl_xor(w.w, 1);
;                         const bool odd = fr & 1;
;                         const unsigned a0 = odd ? oz : w.x, a1 = odd ? ow : w.y;
;                         const unsigned b0 = odd ? w.z : ox, b1 = odd ? w.w : oy;
;                         const unsigned p0 = (a0 & 0xffffu) | (b0 << 16), p1 = (a0 >> 16) | (b0 & 0xffff0000u);
.LBB0_295:
	v_mov_b32_e32 v49, v48
	s_nop 0
	v_mov_b32_e32 v40, v48
	v_mov_b32_e32 v41, v48
	v_pk_mul_f32 v[38:39], v[38:39], v[40:41]
	v_pk_mul_f32 v[36:37], v[36:37], v[48:49]
	v_pk_mul_f32 v[40:41], v[34:35], v[40:41]
	v_pk_mul_f32 v[34:35], v[32:33], v[48:49]
	v_cvt_pk_bf16_f32 v32, v36, v37
	v_cvt_pk_bf16_f32 v33, v38, v39
	v_cvt_pk_bf16_f32 v34, v34, v35
	v_cvt_pk_bf16_f32 v35, v40, v41
	s_and_b64 vcc, exec, s[10:11]
	s_mov_b64 s[0:1], -1
	s_cbranch_vccnz .LBB0_301
	v_cmp_lt_i32_e32 vcc, v134, v186
	s_lshl_b32 s12, s21, 12
	s_cmp_lt_u32 s19, 28
	v_cndmask_b32_e32 v36, v240, v134, vcc
	v_lshlrev_b32_e32 v36, 2, v36
	s_nop 1
	v_mov_b32_dpp v37, v32 quad_perm:[1,0,3,2] row_mask:0xf bank_mask:0xf
	v_mov_b32_dpp v38, v33 quad_perm:[1,0,3,2] row_mask:0xf bank_mask:0xf
	v_mov_b32_dpp v39, v34 quad_perm:[1,0,3,2] row_mask:0xf bank_mask:0xf
	v_mov_b32_dpp v40, v35 quad_perm:[1,0,3,2] row_mask:0xf bank_mask:0xf
	s_cbranch_scc1 .LBB0_298
	s_lshl_b32 s0, s44, 14
	s_add_i32 s1, s12, s40
	s_add_i32 s1, s1, s0
	v_or_b32_e32 v36, s1, v65
	s_mov_b64 s[0:1], s[68:69]
	s_cbranch_execz .LBB0_299
	s_branch .LBB0_300

;     __device__ __forceinline__ void operator()(const f32x4 (&acc)[2][2][4][2], const Unit& u, int wr, int wc, int fr, int fq) const {
;     ...
;             for (int m = 0; m < 4; ++m) {
;                 float s = (part[ai][m][0] + part[ai][m][1]) + (part[ai][m][2] + part[ai][m][3]);
;                 s += __shfl_xor(s, 16); s += __shfl_xor(s, 32);
;                 rstdv[ai][m] = rsqrtf(s * (1.0f / 1024.0f) + RMS_EPS);
;             }
; #pragma unroll
;         for (int ai = 0; ai < 2; ++ai)
; #pragma unroll
;             for (int m = 0; m < 4; ++m) {
;                 const int row = u.pm * BM + ai * HALF + wr * 64 + m * 16 + fr;
;                 const float rstd = rstdv[ai][m];
;                 const int b = row >> 11, s = row & 2047;
; #pragma unroll
;                 for (int bj = 0; bj < 2; ++bj) {
;                     const int tn = 2 * u.pn + bj;
;                     const int cw = 32 * wc + 8 * fq;
;                     const f32x4 v0 = acc[ai][bj][m][0] * rstd, v1 = acc[ai][bj][m][1] * rstd;
;                     u32x4 w; w.x = ::cvt_pk_bf16(v0[0], v0[1]); w.y = ::cvt_pk_bf16(v0[2], v0[3]); w.z = ::cvt_pk_bf16(v1[0], v1[1]); w.w = ::cvt_pk_bf16(v1[2], v1[3]);
;                     if (tn < 24) {
;                         bf16_t* dst;
;                         if (tn < 8) dst = z + (size_t)(tn >> 2) * ZS_KD + ((size_t)((b * 4 + (tn & 3)) * 2048 + s)) * 128 + cw;
;                         else if (tn < 16) dst = z + ZS_QN + (size_t)((tn - 8) >> 2) * (ZS_KN - ZS_QN) + ((size_t)((b * 8 + ((tn - 8) & 3) * 2 + (cw >> 6)) * 2048 + s)) * 64 + (cw & 63);
;                         else dst = z + ZS_GATE + (size_t)row * 1024 + (tn - 16) * 128 + cw;
;                         *(u32x4*)dst = w;
;                     } else {
;                         const unsigned ox = __shfl_xor(w.x, 1), oy = __shfl_xor(w.y, 1), oz = __shfl_xor(w.z, 1), ow = __shfl_xor(w.w, 1);
;                         const bool odd = fr & 1;
;                         const unsigned a0 = odd ? oz : w.x, a1 = odd ? ow : w.y;
;                         const unsigned b0 = odd ? w.z : ox, b1 = odd ? w.w : oy;
;                         const unsigned p0 = (a0 & 0xffffu) | (b0 << 16), p1 = (a0 >> 16) | (b0 & 0xffff0000u);
.LBB0_311:
	s_waitcnt lgkmcnt(0)
	s_nop 0
	v_pk_add_f32 v[32:33], v[128:129], v[130:131]
	s_mov_b32 s0, 0x3a800000
	v_pk_fma_f32 v[32:33], v[32:33], s[0:1], v[236:237] op_sel_hi:[1,0,0]
	v_bitop3_b32 v36, v60, 46, 32 bitop3:0xc8
	v_mul_f32_e32 v34, 0x4b800000, v33
	v_cmp_gt_f32_e32 vcc, s96, v33
	v_cmp_gt_f32_e64 s[12:13], s96, v32
	s_mov_b64 s[0:1], -1
	v_cndmask_b32_e32 v33, v33, v34, vcc
	v_rsq_f32_e32 v33, v33
	s_nop 0
	v_mul_f32_e32 v34, 0x45800000, v33
	v_cndmask_b32_e32 v34, v33, v34, vcc
	v_pk_mul_f32 v[30:31], v[30:31], v[34:35] op_sel_hi:[1,0]
	v_pk_mul_f32 v[28:29], v[28:29], v[34:35] op_sel_hi:[1,0]
	v_pk_mul_f32 v[38:39], v[26:27], v[34:35] op_sel_hi:[1,0]
	v_pk_mul_f32 v[26:27], v[24:25], v[34:35] op_sel_hi:[1,0]
	v_cvt_pk_bf16_f32 v24, v28, v29
	v_cvt_pk_bf16_f32 v25, v30, v31
	v_cvt_pk_bf16_f32 v26, v26, v27
	v_cvt_pk_bf16_f32 v27, v38, v39
	s_and_b64 vcc, exec, s[8:9]
	s_cbranch_vccnz .LBB0_317
	v_cmp_lt_i32_e32 vcc, v134, v186
	s_lshl_b32 s45, s41, 13
	s_cmp_lt_u32 s19, 28
	v_cndmask_b32_e32 v28, v240, v134, vcc
	v_lshlrev_b32_e32 v28, 2, v28
	s_nop 1
	v_mov_b32_dpp v29, v24 quad_perm:[1,0,3,2] row_mask:0xf bank_mask:0xf
	v_mov_b32_dpp v30, v25 quad_perm:[1,0,3,2] row_mask:0xf bank_mask:0xf
	v_mov_b32_dpp v31, v26 quad_perm:[1,0,3,2] row_mask:0xf bank_mask:0xf
	v_mov_b32_dpp v33, v27 quad_perm:[1,0,3,2] row_mask:0xf bank_mask:0xf
	s_cbranch_scc1 .LBB0_314
	s_lshl_b32 s0, s44, 14
	s_add_i32 s1, s45, s40
	s_add_i32 s1, s1, s0
	v_or_b32_e32 v28, s1, v65
	s_mov_b64 s[0:1], s[68:69]
	s_cbranch_execz .LBB0_315
	s_branch .LBB0_316

;     __device__ __forceinline__ void operator()(const f32x4 (&acc)[2][2][4][2], const Unit& u, int wr, int wc, int fr, int fq) const {
;     ...
;                 for (int bj = 0; bj < 2; ++bj) {
;                     const int tn = 2 * u.pn + bj;
;                     const int cw = 32 * wc + 8 * fq;
;                     const f32x4 v0 = acc[ai][bj][m][0] * rstd, v1 = acc[ai][bj][m][1] * rstd;
;                     u32x4 w; w.x = ::cvt_pk_bf16(v0[0], v0[1]); w.y = ::cvt_pk_bf16(v0[2], v0[3]); w.z = ::cvt_pk_bf16(v1[0], v1[1]); w.w = ::cvt_pk_bf16(v1[2], v1[3]);
;                     if (tn < 24) {
;                         bf16_t* dst;
;                         if (tn < 8) dst = z + (size_t)(tn >> 2) * ZS_KD + ((size_t)((b * 4 + (tn & 3)) * 2048 + s)) * 128 + cw;
;                         else if (tn < 16) dst = z + ZS_QN + (size_t)((tn - 8) >> 2) * (ZS_KN - ZS_QN) + ((size_t)((b * 8 + ((tn - 8) & 3) * 2 + (cw >> 6)) * 2048 + s)) * 64 + (cw & 63);
;                         else dst = z + ZS_GATE + (size_t)row * 1024 + (tn - 16) * 128 + cw;
;                         *(u32x4*)dst = w;
;                     } else {
;                         const unsigned ox = __shfl_xor(w.x, 1), oy = __shfl_xor(w.y, 1), oz = __shfl_xor(w.z, 1), ow = __shfl_xor(w.w, 1);
;                         const bool odd = fr & 1;
;                         const unsigned a0 = odd ? oz : w.x, a1 = odd ? ow : w.y;
;                         const unsigned b0 = odd ? w.z : ox, b1 = odd ? w.w : oy;
;                         const unsigned p0 = (a0 & 0xffffu) | (b0 << 16), p1 = (a0 >> 16) | (b0 & 0xffff0000u);
.LBB0_327:
	v_mov_b32_e32 v35, v34
	s_nop 0
	v_mov_b32_e32 v24, v34
	v_mov_b32_e32 v25, v34
	v_pk_mul_f32 v[22:23], v[22:23], v[24:25]
	v_pk_mul_f32 v[20:21], v[20:21], v[34:35]
	v_pk_mul_f32 v[24:25], v[18:19], v[24:25]
	v_pk_mul_f32 v[18:19], v[16:17], v[34:35]
	v_cvt_pk_bf16_f32 v16, v20, v21
	v_cvt_pk_bf16_f32 v17, v22, v23
	v_cvt_pk_bf16_f32 v18, v18, v19
	v_cvt_pk_bf16_f32 v19, v24, v25
	s_and_b64 vcc, exec, s[10:11]
	s_mov_b64 s[0:1], -1
	s_cbranch_vccnz .LBB0_333
	v_cmp_lt_i32_e32 vcc, v134, v186
	s_lshl_b32 s45, s21, 12
	s_cmp_lt_u32 s19, 28
	v_cndmask_b32_e32 v20, v240, v134, vcc
	v_lshlrev_b32_e32 v20, 2, v20
	s_nop 1
	v_mov_b32_dpp v21, v16 quad_perm:[1,0,3,2] row_mask:0xf bank_mask:0xf
	v_mov_b32_dpp v22, v17 quad_perm:[1,0,3,2] row_mask:0xf bank_mask:0xf
	v_mov_b32_dpp v23, v18 quad_perm:[1,0,3,2] row_mask:0xf bank_mask:0xf
	v_mov_b32_dpp v24, v19 quad_perm:[1,0,3,2] row_mask:0xf bank_mask:0xf
	s_cbranch_scc1 .LBB0_330
	s_lshl_b32 s0, s44, 14
	s_add_i32 s1, s45, s40
	s_add_i32 s1, s1, s0
	v_or_b32_e32 v20, s1, v65
	s_mov_b64 s[0:1], s[68:69]
	s_cbranch_execz .LBB0_331
	s_branch .LBB0_332

;     __device__ __forceinline__ void operator()(const f32x4 (&acc)[2][2][4][2], const Unit& u, int wr, int wc, int fr, int fq) const {
;     ...
;             for (int m = 0; m < 4; ++m) {
;                 float s = (part[ai][m][0] + part[ai][m][1]) + (part[ai][m][2] + part[ai][m][3]);
;                 s += __shfl_xor(s, 16); s += __shfl_xor(s, 32);
;                 rstdv[ai][m] = rsqrtf(s * (1.0f / 1024.0f) + RMS_EPS);
;             }
; #pragma unroll
;         for (int ai = 0; ai < 2; ++ai)
; #pragma unroll
;             for (int m = 0; m < 4; ++m) {
;                 const int row = u.pm * BM + ai * HALF + wr * 64 + m * 16 + fr;
;                 const float rstd = rstdv[ai][m];
;                 const int b = row >> 11, s = row & 2047;
; #pragma unroll
;                 for (int bj = 0; bj < 2; ++bj) {
;                     const int tn = 2 * u.pn + bj;
;                     const int cw = 32 * wc + 8 * fq;
;                     const f32x4 v0 = acc[ai][bj][m][0] * rstd, v1 = acc[ai][bj][m][1] * rstd;
;                     u32x4 w; w.x = ::cvt_pk_bf16(v0[0], v0[1]); w.y = ::cvt_pk_bf16(v0[2], v0[3]); w.z = ::cvt_pk_bf16(v1[0], v1[1]); w.w = ::cvt_pk_bf16(v1[2], v1[3]);
;                     if (tn < 24) {
;                         bf16_t* dst;
;                         if (tn < 8) dst = z + (size_t)(tn >> 2) * ZS_KD + ((size_t)((b * 4 + (tn & 3)) * 2048 + s)) * 128 + cw;
;                         else if (tn < 16) dst = z + ZS_QN + (size_t)((tn - 8) >> 2) * (ZS_KN - ZS_QN) + ((size_t)((b * 8 + ((tn - 8) & 3) * 2 + (cw >> 6)) * 2048 + s)) * 64 + (cw & 63);
;                         else dst = z + ZS_GATE + (size_t)row * 1024 + (tn - 16) * 128 + cw;
;                         *(u32x4*)dst = w;
;                     } else {
;                         const unsigned ox = __shfl_xor(w.x, 1), oy = __shfl_xor(w.y, 1), oz = __shfl_xor(w.z, 1), ow = __shfl_xor(w.w, 1);
;                         const bool odd = fr & 1;
;                         const unsigned a0 = odd ? oz : w.x, a1 = odd ? ow : w.y;
;                         const unsigned b0 = odd ? w.z : ox, b1 = odd ? w.w : oy;
;                         const unsigned p0 = (a0 & 0xffffu) | (b0 << 16), p1 = (a0 >> 16) | (b0 & 0xffff0000u);
.LBB0_343:
	s_nop 1
	v_mul_f32_e32 v16, 0x4b800000, v32
	v_cndmask_b32_e64 v16, v32, v16, s[12:13]
	v_rsq_f32_e32 v16, v16
	v_bitop3_b32 v19, v60, 62, 48 bitop3:0xc8
	s_and_b64 vcc, exec, s[8:9]
	s_mov_b64 s[0:1], -1
	v_mul_f32_e32 v17, 0x45800000, v16
	v_cndmask_b32_e64 v16, v16, v17, s[12:13]
	v_pk_mul_f32 v[14:15], v[14:15], v[16:17] op_sel_hi:[1,0]
	v_pk_mul_f32 v[12:13], v[12:13], v[16:17] op_sel_hi:[1,0]
	v_pk_mul_f32 v[20:21], v[10:11], v[16:17] op_sel_hi:[1,0]
	v_pk_mul_f32 v[10:11], v[8:9], v[16:17] op_sel_hi:[1,0]
	v_cvt_pk_bf16_f32 v8, v12, v13
	v_cvt_pk_bf16_f32 v9, v14, v15
	v_cvt_pk_bf16_f32 v10, v10, v11
	v_cvt_pk_bf16_f32 v11, v20, v21
	s_cbranch_vccnz .LBB0_349
	v_cmp_lt_i32_e32 vcc, v134, v186
	s_lshl_b32 s8, s41, 13
	s_cmp_lt_u32 s19, 28
	v_cndmask_b32_e32 v12, v240, v134, vcc
	v_lshlrev_b32_e32 v12, 2, v12
	s_nop 1
	v_mov_b32_dpp v13, v8 quad_perm:[1,0,3,2] row_mask:0xf bank_mask:0xf
	v_mov_b32_dpp v14, v9 quad_perm:[1,0,3,2] row_mask:0xf bank_mask:0xf
	v_mov_b32_dpp v15, v10 quad_perm:[1,0,3,2] row_mask:0xf bank_mask:0xf
	v_mov_b32_dpp v17, v11 quad_perm:[1,0,3,2] row_mask:0xf bank_mask:0xf
	s_cbranch_scc1 .LBB0_346
	s_lshl_b32 s0, s44, 14
	s_add_i32 s1, s8, s40
	s_add_i32 s1, s1, s0
	v_or_b32_e32 v12, s1, v65
	s_mov_b64 s[0:1], s[68:69]
	s_cbranch_execz .LBB0_347
	s_branch .LBB0_348

;     __device__ __forceinline__ void operator()(const f32x4 (&acc)[2][2][4][2], const Unit& u, int wr, int wc, int fr, int fq) const {
;     ...
;                 for (int bj = 0; bj < 2; ++bj) {
;                     const int tn = 2 * u.pn + bj;
;                     const int cw = 32 * wc + 8 * fq;
;                     const f32x4 v0 = acc[ai][bj][m][0] * rstd, v1 = acc[ai][bj][m][1] * rstd;
;                     u32x4 w; w.x = ::cvt_pk_bf16(v0[0], v0[1]); w.y = ::cvt_pk_bf16(v0[2], v0[3]); w.z = ::cvt_pk_bf16(v1[0], v1[1]); w.w = ::cvt_pk_bf16(v1[2], v1[3]);
;                     if (tn < 24) {
;                         bf16_t* dst;
;                         if (tn < 8) dst = z + (size_t)(tn >> 2) * ZS_KD + ((size_t)((b * 4 + (tn & 3)) * 2048 + s)) * 128 + cw;
;                         else if (tn < 16) dst = z + ZS_QN + (size_t)((tn - 8) >> 2) * (ZS_KN - ZS_QN) + ((size_t)((b * 8 + ((tn - 8) & 3) * 2 + (cw >> 6)) * 2048 + s)) * 64 + (cw & 63);
;                         else dst = z + ZS_GATE + (size_t)row * 1024 + (tn - 16) * 128 + cw;
;                         *(u32x4*)dst = w;
;                     } else {
;                         const unsigned ox = __shfl_xor(w.x, 1), oy = __shfl_xor(w.y, 1), oz = __shfl_xor(w.z, 1), ow = __shfl_xor(w.w, 1);
;                         const bool odd = fr & 1;
;                         const unsigned a0 = odd ? oz : w.x, a1 = odd ? ow : w.y;
;                         const unsigned b0 = odd ? w.z : ox, b1 = odd ? w.w : oy;
;                         const unsigned p0 = (a0 & 0xffffu) | (b0 << 16), p1 = (a0 >> 16) | (b0 & 0xffff0000u);
.LBB0_362:
	v_cmp_lt_i32_e32 vcc, v134, v186
	s_lshl_b32 s8, s21, 12
	s_cmp_lt_u32 s19, 28
	v_cndmask_b32_e32 v4, v240, v134, vcc
	v_lshlrev_b32_e32 v4, 2, v4
	s_nop 1
	v_mov_b32_dpp v5, v0 quad_perm:[1,0,3,2] row_mask:0xf bank_mask:0xf
	v_mov_b32_dpp v6, v1 quad_perm:[1,0,3,2] row_mask:0xf bank_mask:0xf
	v_mov_b32_dpp v7, v2 quad_perm:[1,0,3,2] row_mask:0xf bank_mask:0xf
	v_mov_b32_dpp v8, v3 quad_perm:[1,0,3,2] row_mask:0xf bank_mask:0xf
	s_cbranch_scc1 .LBB0_364
	s_lshl_b32 s0, s44, 14
	s_add_i32 s1, s8, s40
	s_add_i32 s1, s1, s0
	v_or_b32_e32 v4, s1, v65
	s_mov_b64 s[0:1], s[68:69]
	s_cbranch_execz .LBB0_365
	s_branch .LBB0_366
